# prompt pool units: z staging waits vmcnt(32) so the LDS staging, barrier and window sums run under the 32 weight-fragment loads
# speedup vs baseline: 1.0051x; 1.0051x over previous
.LBB0_555:
	s_waitcnt vmcnt(0)
	v_and_b32_e32 v212, 63, v204
	v_lshrrev_b32_e32 v213, 4, v212
	v_and_b32_e32 v212, 15, v212
	v_lshlrev_b32_e32 v213, 2, v213
	v_lshl_or_b32 v212, v212, 4, v213
	ds_bpermute_b32 v2, v212, v2
	ds_bpermute_b32 v3, v212, v3
	ds_bpermute_b32 v4, v212, v4
	ds_bpermute_b32 v5, v212, v5
	ds_bpermute_b32 v6, v212, v6
	ds_bpermute_b32 v7, v212, v7
	ds_bpermute_b32 v8, v212, v8
	ds_bpermute_b32 v9, v212, v9
	ds_bpermute_b32 v10, v212, v10
	ds_bpermute_b32 v11, v212, v11
	ds_bpermute_b32 v12, v212, v12
	ds_bpermute_b32 v13, v212, v13
	ds_bpermute_b32 v14, v212, v14
	ds_bpermute_b32 v15, v212, v15
	ds_bpermute_b32 v16, v212, v16
	ds_bpermute_b32 v17, v212, v17
	s_waitcnt lgkmcnt(0)
	ds_bpermute_b32 v18, v212, v18
	ds_bpermute_b32 v19, v212, v19
	ds_bpermute_b32 v20, v212, v20
	ds_bpermute_b32 v21, v212, v21
	ds_bpermute_b32 v22, v212, v22
	ds_bpermute_b32 v23, v212, v23
	ds_bpermute_b32 v24, v212, v24
	ds_bpermute_b32 v25, v212, v25
	ds_bpermute_b32 v26, v212, v26
	ds_bpermute_b32 v27, v212, v27
	ds_bpermute_b32 v28, v212, v28
	ds_bpermute_b32 v29, v212, v29
	ds_bpermute_b32 v30, v212, v30
	ds_bpermute_b32 v31, v212, v31
	ds_bpermute_b32 v32, v212, v32
	ds_bpermute_b32 v33, v212, v33
	s_waitcnt lgkmcnt(0)
	ds_bpermute_b32 v34, v212, v34
	ds_bpermute_b32 v35, v212, v35
	ds_bpermute_b32 v36, v212, v36
	ds_bpermute_b32 v37, v212, v37
	ds_bpermute_b32 v38, v212, v38
	ds_bpermute_b32 v39, v212, v39
	ds_bpermute_b32 v40, v212, v40
	ds_bpermute_b32 v41, v212, v41
	ds_bpermute_b32 v42, v212, v42
	ds_bpermute_b32 v43, v212, v43
	ds_bpermute_b32 v44, v212, v44
	ds_bpermute_b32 v45, v212, v45
	ds_bpermute_b32 v46, v212, v46
	ds_bpermute_b32 v47, v212, v47
	ds_bpermute_b32 v48, v212, v48
	ds_bpermute_b32 v49, v212, v49
	s_waitcnt lgkmcnt(0)
	ds_bpermute_b32 v50, v212, v50
	ds_bpermute_b32 v51, v212, v51
	ds_bpermute_b32 v52, v212, v52
	ds_bpermute_b32 v53, v212, v53
	ds_bpermute_b32 v54, v212, v54
	ds_bpermute_b32 v55, v212, v55
	ds_bpermute_b32 v56, v212, v56
	ds_bpermute_b32 v57, v212, v57
	ds_bpermute_b32 v58, v212, v58
	ds_bpermute_b32 v59, v212, v59
	ds_bpermute_b32 v60, v212, v60
	ds_bpermute_b32 v61, v212, v61
	ds_bpermute_b32 v62, v212, v62
	ds_bpermute_b32 v63, v212, v63
	ds_bpermute_b32 v64, v212, v64
	ds_bpermute_b32 v65, v212, v65
	s_waitcnt lgkmcnt(0)
	ds_bpermute_b32 v66, v212, v66
	ds_bpermute_b32 v67, v212, v67
	ds_bpermute_b32 v68, v212, v68
	ds_bpermute_b32 v69, v212, v69
	ds_bpermute_b32 v70, v212, v70
	ds_bpermute_b32 v71, v212, v71
	ds_bpermute_b32 v72, v212, v72
	ds_bpermute_b32 v73, v212, v73
	ds_bpermute_b32 v74, v212, v74
	ds_bpermute_b32 v75, v212, v75
	ds_bpermute_b32 v76, v212, v76
	ds_bpermute_b32 v77, v212, v77
	ds_bpermute_b32 v78, v212, v78
	ds_bpermute_b32 v79, v212, v79
	ds_bpermute_b32 v80, v212, v80
	ds_bpermute_b32 v81, v212, v81
	s_waitcnt lgkmcnt(0)
	ds_bpermute_b32 v82, v212, v82
	ds_bpermute_b32 v83, v212, v83
	ds_bpermute_b32 v84, v212, v84
	ds_bpermute_b32 v85, v212, v85
	ds_bpermute_b32 v86, v212, v86
	ds_bpermute_b32 v87, v212, v87
	ds_bpermute_b32 v88, v212, v88
	ds_bpermute_b32 v89, v212, v89
	ds_bpermute_b32 v90, v212, v90
	ds_bpermute_b32 v91, v212, v91
	ds_bpermute_b32 v92, v212, v92
	ds_bpermute_b32 v93, v212, v93
	ds_bpermute_b32 v94, v212, v94
	ds_bpermute_b32 v95, v212, v95
	ds_bpermute_b32 v96, v212, v96
	ds_bpermute_b32 v97, v212, v97
	s_waitcnt lgkmcnt(0)
	ds_bpermute_b32 v98, v212, v98
	ds_bpermute_b32 v99, v212, v99
	ds_bpermute_b32 v100, v212, v100
	ds_bpermute_b32 v101, v212, v101
	ds_bpermute_b32 v102, v212, v102
	ds_bpermute_b32 v103, v212, v103
	ds_bpermute_b32 v104, v212, v104
	ds_bpermute_b32 v105, v212, v105
	ds_bpermute_b32 v106, v212, v106
	ds_bpermute_b32 v107, v212, v107
	ds_bpermute_b32 v108, v212, v108
	ds_bpermute_b32 v109, v212, v109
	ds_bpermute_b32 v110, v212, v110
	ds_bpermute_b32 v111, v212, v111
	ds_bpermute_b32 v112, v212, v112
	ds_bpermute_b32 v113, v212, v113
	s_waitcnt lgkmcnt(0)
	ds_bpermute_b32 v114, v212, v114
	ds_bpermute_b32 v115, v212, v115
	ds_bpermute_b32 v116, v212, v116
	ds_bpermute_b32 v117, v212, v117
	ds_bpermute_b32 v118, v212, v118
	ds_bpermute_b32 v119, v212, v119
	ds_bpermute_b32 v120, v212, v120
	ds_bpermute_b32 v121, v212, v121
	ds_bpermute_b32 v122, v212, v122
	ds_bpermute_b32 v123, v212, v123
	ds_bpermute_b32 v124, v212, v124
	ds_bpermute_b32 v125, v212, v125
	ds_bpermute_b32 v126, v212, v126
	ds_bpermute_b32 v127, v212, v127
	ds_bpermute_b32 v128, v212, v128
	ds_bpermute_b32 v129, v212, v129
	s_waitcnt lgkmcnt(0)
	s_add_i32 s0, s19, s22
	v_add3_u32 v0, s0, 1, v176
	v_min_i32_e32 v0, s24, v0
	v_cvt_f32_i32_e32 v0, v0
	s_lshl_b32 s72, s23, 1
	v_div_scale_f32 v212, s[0:1], v0, v0, 1.0
	v_rcp_f32_e32 v213, v212
	v_div_scale_f32 v214, vcc, 1.0, v0, 1.0
	v_fma_f32 v215, -v212, v213, 1.0
	v_fmac_f32_e32 v213, v215, v213
	v_mul_f32_e32 v215, v214, v213
	v_fma_f32 v222, -v212, v215, v214
	v_fmac_f32_e32 v215, v222, v213
	v_fma_f32 v212, -v212, v215, v214
	v_div_fmas_f32 v212, v212, v213, v215
	v_div_fixup_f32 v0, v212, v0, 1.0
	v_pk_fma_f32 v[138:139], v[0:1], v[144:145], v[138:139] op_sel_hi:[0,1,1] neg_lo:[0,0,1] neg_hi:[0,0,1]
	v_pk_fma_f32 v[136:137], v[0:1], v[142:143], v[136:137] op_sel_hi:[0,1,1] neg_lo:[0,0,1] neg_hi:[0,0,1]
	v_pk_fma_f32 v[134:135], v[0:1], v[140:141], v[134:135] op_sel_hi:[0,1,1] neg_lo:[0,0,1] neg_hi:[0,0,1]
	v_pk_fma_f32 v[130:131], v[0:1], v[132:133], v[130:131] op_sel_hi:[0,1,1] neg_lo:[0,0,1] neg_hi:[0,0,1]
	v_cvt_pk_bf16_f32 v138, v138, v139
	v_cvt_pk_bf16_f32 v139, v136, v137
	v_cvt_pk_bf16_f32 v140, v134, v135
	v_cvt_pk_bf16_f32 v141, v130, v131
	v_pk_fma_f32 v[154:155], v[0:1], v[160:161], v[154:155] op_sel_hi:[0,1,1] neg_lo:[0,0,1] neg_hi:[0,0,1]
	v_pk_fma_f32 v[152:153], v[0:1], v[158:159], v[152:153] op_sel_hi:[0,1,1] neg_lo:[0,0,1] neg_hi:[0,0,1]
	v_mfma_f32_16x16x32_bf16 v[94:97], v[94:97], v[138:141], 0
	v_fma_f32 v150, v0, v156, -v150
	v_fma_f32 v151, v0, v157, -v151
	v_pk_fma_f32 v[146:147], v[0:1], v[146:147], v[148:149] op_sel_hi:[0,1,1] neg_lo:[0,0,1] neg_hi:[0,0,1]
	v_cvt_pk_bf16_f32 v154, v154, v155
	v_mfma_f32_16x16x32_bf16 v[38:41], v[38:41], v[138:141], 0
	v_cvt_pk_bf16_f32 v155, v152, v153
	v_cvt_pk_bf16_f32 v156, v150, v151
	v_cvt_pk_bf16_f32 v157, v146, v147
	v_pk_fma_f32 v[170:171], v[0:1], v[186:187], v[170:171] op_sel_hi:[0,1,1] neg_lo:[0,0,1] neg_hi:[0,0,1]
	v_pk_fma_f32 v[174:175], v[0:1], v[174:175], v[168:169] op_sel_hi:[0,1,1] neg_lo:[0,0,1] neg_hi:[0,0,1]
	v_mfma_f32_16x16x32_bf16 v[78:81], v[78:81], v[154:157], v[94:97]
	v_fma_f32 v166, v0, v172, -v166
	v_fma_f32 v167, v0, v173, -v167
	v_pk_fma_f32 v[162:163], v[0:1], v[162:163], v[164:165] op_sel_hi:[0,1,1] neg_lo:[0,0,1] neg_hi:[0,0,1]
	v_cvt_pk_bf16_f32 v168, v170, v171
	v_mfma_f32_16x16x32_bf16 v[38:41], v[42:45], v[154:157], v[38:41]
	v_cvt_pk_bf16_f32 v169, v174, v175
	v_cvt_pk_bf16_f32 v170, v166, v167
	v_cvt_pk_bf16_f32 v171, v162, v163
	v_pk_fma_f32 v[130:131], v[0:1], v[202:203], v[188:189] op_sel_hi:[0,1,1] neg_lo:[0,0,1] neg_hi:[0,0,1]
	v_pk_fma_f32 v[94:95], v[0:1], v[200:201], v[192:193] op_sel_hi:[0,1,1] neg_lo:[0,0,1] neg_hi:[0,0,1]
	v_mfma_f32_16x16x32_bf16 v[66:69], v[66:69], v[168:171], v[78:81]
	v_cvt_pk_bf16_f32 v130, v130, v131
	v_cvt_pk_bf16_f32 v131, v94, v95
	v_pk_fma_f32 v[94:95], v[0:1], v[198:199], v[194:195] op_sel_hi:[0,1,1] neg_lo:[0,0,1] neg_hi:[0,0,1]
	v_mfma_f32_16x16x32_bf16 v[38:41], v[46:49], v[168:171], v[38:41]
	v_fma_f32 v78, v0, v190, -v196
	v_fma_f32 v79, v0, v191, -v197
	v_cvt_pk_bf16_f32 v132, v94, v95
	v_cvt_pk_bf16_f32 v133, v78, v79
	v_mfma_f32_16x16x32_bf16 v[42:45], v[102:105], v[138:141], 0
	v_or_b32_e32 v0, s21, v176
	v_mfma_f32_16x16x32_bf16 v[34:37], v[34:37], v[130:133], v[66:69]
	v_mfma_f32_16x16x32_bf16 v[66:69], v[126:129], v[138:141], 0
	v_mfma_f32_16x16x32_bf16 v[38:41], v[50:53], v[130:133], v[38:41]
	s_nop 5
	v_cvt_pk_bf16_f32 v34, v34, v35
	v_cvt_pk_bf16_f32 v35, v36, v37
	v_mfma_f32_16x16x32_bf16 v[46:49], v[54:57], v[138:141], 0
	v_add_u32_e32 v54, s19, v0
	v_ashrrev_i32_e32 v55, 31, v54
	v_lshlrev_b64 v[54:55], 11, v[54:55]
	v_mfma_f32_16x16x32_bf16 v[50:53], v[106:109], v[138:141], 0
	v_lshl_add_u64 v[54:55], s[76:77], 0, v[54:55]
	v_lshl_add_u64 v[54:55], v[54:55], 0, s[72:73]
	v_lshlrev_b32_e32 v0, 3, v225
	v_mfma_f32_16x16x32_bf16 v[30:33], v[30:33], v[138:141], 0
	v_lshl_add_u64 v[54:55], v[54:55], 0, v[0:1]
	global_store_dwordx2 v[54:55], v[34:35], off
	v_mfma_f32_16x16x32_bf16 v[14:17], v[14:17], v[138:141], 0
	v_mfma_f32_16x16x32_bf16 v[42:45], v[82:85], v[154:157], v[42:45]
	v_mfma_f32_16x16x32_bf16 v[66:69], v[70:73], v[154:157], v[66:69]
	v_mfma_f32_16x16x32_bf16 v[46:49], v[58:61], v[154:157], v[46:49]
	v_mfma_f32_16x16x32_bf16 v[50:53], v[110:113], v[154:157], v[50:53]
	v_mfma_f32_16x16x32_bf16 v[26:29], v[26:29], v[154:157], v[30:33]
	v_mfma_f32_16x16x32_bf16 v[10:13], v[10:13], v[154:157], v[14:17]
	v_mfma_f32_16x16x32_bf16 v[42:45], v[86:89], v[168:171], v[42:45]
	v_mfma_f32_16x16x32_bf16 v[66:69], v[74:77], v[168:171], v[66:69]
	v_mfma_f32_16x16x32_bf16 v[46:49], v[62:65], v[168:171], v[46:49]
	v_mfma_f32_16x16x32_bf16 v[50:53], v[98:101], v[168:171], v[50:53]
	v_mfma_f32_16x16x32_bf16 v[22:25], v[22:25], v[168:171], v[26:29]
	v_mfma_f32_16x16x32_bf16 v[6:9], v[6:9], v[168:171], v[10:13]
	s_nop 1
	v_cvt_pk_bf16_f32 v26, v38, v39
	v_cvt_pk_bf16_f32 v27, v40, v41
	global_store_dwordx2 v[54:55], v[26:27], off offset:64
	v_mfma_f32_16x16x32_bf16 v[42:45], v[90:93], v[130:133], v[42:45]
	v_mfma_f32_16x16x32_bf16 v[66:69], v[122:125], v[130:133], v[66:69]
	v_mfma_f32_16x16x32_bf16 v[46:49], v[114:117], v[130:133], v[46:49]
	v_mfma_f32_16x16x32_bf16 v[50:53], v[118:121], v[130:133], v[50:53]
	s_nop 5
	v_cvt_pk_bf16_f32 v30, v66, v67
	v_cvt_pk_bf16_f32 v31, v68, v69
	global_store_dwordx2 v[54:55], v[30:31], off offset:32
	v_mfma_f32_16x16x32_bf16 v[18:21], v[18:21], v[130:133], v[22:25]
	v_mfma_f32_16x16x32_bf16 v[2:5], v[2:5], v[130:133], v[6:9]
	s_nop 1
	v_cvt_pk_bf16_f32 v22, v42, v43
	v_cvt_pk_bf16_f32 v23, v44, v45
	global_store_dwordx2 v[54:55], v[22:23], off offset:96
	v_cvt_pk_bf16_f32 v22, v46, v47
	v_cvt_pk_bf16_f32 v23, v48, v49
	v_cvt_pk_bf16_f32 v14, v50, v51
	v_cvt_pk_bf16_f32 v15, v52, v53
	v_cvt_pk_bf16_f32 v10, v18, v19
	v_cvt_pk_bf16_f32 v11, v20, v21
	v_cvt_pk_bf16_f32 v2, v2, v3
	v_cvt_pk_bf16_f32 v3, v4, v5
	global_store_dwordx2 v[54:55], v[22:23], off offset:128
	global_store_dwordx2 v[54:55], v[14:15], off offset:160
	global_store_dwordx2 v[54:55], v[10:11], off offset:192
	global_store_dwordx2 v[54:55], v[2:3], off offset:224

.LBB0_634:
	s_or_b64 exec, exec, s[48:49]
	s_mov_b32 s37, s73
	s_lshl_b64 s[24:25], s[36:37], 15
	s_add_u32 s24, s51, s24
	v_readlane_b32 s12, v253, 20
	v_bfe_u32 v225, v151, 4, 2
	s_addc_u32 s25, s12, s25
	v_lshlrev_b32_e32 v0, 8, v176
	v_lshl_add_u64 v[2:3], s[24:25], 0, v[0:1]
	v_lshlrev_b32_e32 v0, 4, v225
	v_lshl_add_u64 v[2:3], v[2:3], 0, v[0:1]
	v_and_b32_e32 v10, 63, v204
	v_lshrrev_b32_e32 v11, 2, v10
	v_and_b32_e32 v12, 15, v10
	v_sub_u32_e32 v11, v11, v12
	v_lshlrev_b32_e32 v11, 8, v11
	v_and_b32_e32 v12, 3, v10
	v_lshrrev_b32_e32 v13, 4, v10
	v_sub_u32_e32 v12, v12, v13
	v_lshl_add_u32 v10, v12, 4, v11
	v_ashrrev_i32_e32 v11, 31, v10
	v_lshl_add_u64 v[2:3], v[2:3], 0, v[10:11]
	s_movk_i32 s12, 0x1000
	v_add_co_u32_e32 v4, vcc, s12, v2
	s_movk_i32 s12, 0x2000
	s_nop 0
	v_addc_co_u32_e32 v5, vcc, 0, v3, vcc
	v_add_co_u32_e32 v126, vcc, s12, v2
	s_movk_i32 s12, 0x3000
	s_nop 0
	v_addc_co_u32_e32 v127, vcc, 0, v3, vcc
	v_add_co_u32_e32 v6, vcc, s12, v2
	s_movk_i32 s12, 0x4000
	s_nop 0
	v_addc_co_u32_e32 v7, vcc, 0, v3, vcc
	v_add_co_u32_e32 v8, vcc, s12, v2
	s_movk_i32 s12, 0x5000
	s_nop 0
	v_addc_co_u32_e32 v9, vcc, 0, v3, vcc
	global_load_dwordx4 v[94:97], v[2:3], off
	global_load_dwordx4 v[78:81], v[2:3], off offset:64
	global_load_dwordx4 v[66:69], v[2:3], off offset:128
	global_load_dwordx4 v[34:37], v[2:3], off offset:192
	global_load_dwordx4 v[70:73], v[4:5], off offset:64
	global_load_dwordx4 v[74:77], v[4:5], off offset:128
	global_load_dwordx4 v[38:41], v[126:127], off
	global_load_dwordx4 v[42:45], v[126:127], off offset:64
	global_load_dwordx4 v[46:49], v[126:127], off offset:128
	global_load_dwordx4 v[50:53], v[126:127], off offset:192
	global_load_dwordx4 v[122:125], v[4:5], off offset:192
	global_load_dwordx4 v[82:85], v[6:7], off offset:64
	global_load_dwordx4 v[86:89], v[6:7], off offset:128
	global_load_dwordx4 v[90:93], v[6:7], off offset:192
	global_load_dwordx4 v[102:105], v[8:9], off offset:-4096
	global_load_dwordx4 v[54:57], v[8:9], off
	global_load_dwordx4 v[58:61], v[8:9], off offset:64
	global_load_dwordx4 v[62:65], v[8:9], off offset:128
	v_add_co_u32_e32 v4, vcc, s12, v2
	s_movk_i32 s12, 0x6000
	s_nop 0
	v_addc_co_u32_e32 v5, vcc, 0, v3, vcc
	v_add_co_u32_e32 v6, vcc, s12, v2
	v_lshlrev_b32_e32 v150, 4, v151
	s_nop 0
	v_addc_co_u32_e32 v7, vcc, 0, v3, vcc
	global_load_dwordx4 v[114:117], v[8:9], off offset:192
	global_load_dwordx4 v[106:109], v[6:7], off offset:-4096
	global_load_dwordx4 v[110:113], v[4:5], off offset:64
	global_load_dwordx4 v[98:101], v[4:5], off offset:128
	global_load_dwordx4 v[30:33], v[6:7], off
	global_load_dwordx4 v[26:29], v[6:7], off offset:64
	global_load_dwordx4 v[22:25], v[6:7], off offset:128
	global_load_dwordx4 v[18:21], v[6:7], off offset:192
	v_add_co_u32_e32 v2, vcc, 0x7000, v2
	v_and_b32_e32 v150, 0xf0, v150
	s_nop 0
	v_addc_co_u32_e32 v3, vcc, 0, v3, vcc
	global_load_dwordx4 v[118:121], v[4:5], off offset:192
	global_load_dwordx4 v[14:17], v[2:3], off
	global_load_dwordx4 v[10:13], v[2:3], off offset:64
	global_load_dwordx4 v[6:9], v[2:3], off offset:128
	s_nop 0
	global_load_dwordx4 v[126:129], v[126:127], off offset:-4096
	s_nop 0
	global_load_dwordx4 v[2:5], v[2:3], off offset:192
	v_add_u32_e32 v150, 0, v150
	s_and_saveexec_b64 s[48:49], s[0:1]
	s_cbranch_execz .LBB0_644
	s_movk_i32 s0, 0x120
	v_mad_u64_u32 v[158:159], s[0:1], v152, s0, v[150:151]
	s_waitcnt vmcnt(32)
	ds_write_b128 v158, v[134:137]
	s_or_b64 exec, exec, s[48:49]
	s_and_saveexec_b64 s[0:1], s[38:39]
	s_cbranch_execnz .LBB0_645

.LBB0_637:
	s_movk_i32 s12, 0x120
	s_waitcnt vmcnt(32)
	v_mad_u64_u32 v[134:135], s[24:25], v154, s12, v[150:151]
	ds_write_b128 v134, v[130:133]
	s_or_b64 exec, exec, s[0:1]
	s_and_saveexec_b64 s[0:1], s[44:45]
	s_cbranch_execnz .LBB0_647

.LBB0_639:
	s_movk_i32 s12, 0x120
	s_waitcnt vmcnt(32)
	v_mad_u64_u32 v[130:131], s[24:25], v156, s12, v[150:151]
	ds_write_b128 v130, v[142:145]
.LBB0_640:
	s_or_b64 exec, exec, s[0:1]
	v_readfirstlane_b32 s0, v151
	s_ashr_i32 s0, s0, 2
	s_and_b32 s19, s0, -16
	s_cmpk_gt_i32 s19, 0x7f
	s_waitcnt lgkmcnt(0)
	s_barrier
	s_cbranch_scc1 .LBB0_556
	s_or_b32 s0, s0, 15
	s_lshl_b32 s24, 2, s36
	v_add_u32_e32 v130, s0, v176
	s_movk_i32 s0, 0x120
	s_cmp_gt_i32 s24, 0
	v_add_u32_e32 v131, 0, v0
	v_mul_lo_u32 v226, v130, s0
	s_cselect_b64 s[38:39], -1, 0
	s_cmp_lt_i32 s24, 1
	v_add_u32_e32 v188, v131, v226
	s_cbranch_scc1 .LBB0_648
	ds_read_b128 v[130:133], v188
	v_readlane_b32 s1, v255, 51
	s_add_i32 s0, s24, -1
	s_waitcnt lgkmcnt(0)
	v_and_b32_e32 v139, 0xffff0000, v130
	v_lshlrev_b32_e32 v138, 16, v130
	v_and_b32_e32 v137, 0xffff0000, v131
	v_lshlrev_b32_e32 v136, 16, v131
	v_and_b32_e32 v135, 0xffff0000, v132
	v_lshlrev_b32_e32 v134, 16, v132
	v_and_b32_e32 v131, 0xffff0000, v133
	v_lshlrev_b32_e32 v130, 16, v133
	v_pk_add_f32 v[132:133], v[130:131], 0 op_sel_hi:[1,0]
	v_pk_add_f32 v[140:141], v[134:135], 0 op_sel_hi:[1,0]
	v_pk_add_f32 v[142:143], v[136:137], 0 op_sel_hi:[1,0]
	v_pk_add_f32 v[144:145], v[138:139], 0 op_sel_hi:[1,0]
	v_add3_u32 v146, v226, v0, s1

.LBB0_645:
	s_movk_i32 s12, 0x120
	s_waitcnt vmcnt(32)
	v_mad_u64_u32 v[134:135], s[24:25], v153, s12, v[150:151]
	ds_write_b128 v134, v[138:141]
	s_or_b64 exec, exec, s[0:1]
	s_and_saveexec_b64 s[0:1], s[42:43]
	s_cbranch_execnz .LBB0_637

.LBB0_647:
	s_movk_i32 s12, 0x120
	s_waitcnt vmcnt(32)
	v_mad_u64_u32 v[130:131], s[24:25], v155, s12, v[150:151]
	ds_write_b128 v130, v[146:149]
	s_or_b64 exec, exec, s[0:1]
	s_and_saveexec_b64 s[0:1], s[46:47]
	s_cbranch_execnz .LBB0_639
	s_branch .LBB0_640
